# adds: group B issues the first four K-fragment reads of QK(t) in front of the last four MFMAs of P.V(t-1)
# baseline (speedup 1.0000x reference)
.Lkvdma_skip:
	s_mov_b32 s70, s36
	s_cmp_eq_u32 s57, 2
	s_cselect_b64 s[42:43], -1, 0
	s_xor_b64 s[74:75], s[80:81], -1
	s_or_b64 s[42:43], s[74:75], s[42:43]
	s_and_b64 vcc, exec, s[42:43]
	s_cbranch_vccnz .LBB0_148
	s_setprio 1
	v_lshl_add_u32 v210, s37, 14, v218
	s_waitcnt lgkmcnt(0)
	s_nop 0
	v_mfma_f32_32x32x16_bf16 v[32:47], v[76:79], v[154:157], v[32:47]
	ds_read_b64_tr_b16 v[80:81], v210 offset:0x200
	ds_read_b64_tr_b16 v[82:83], v210 offset:0xa00
	v_mfma_f32_32x32x16_bf16 v[32:47], v[72:75], v[158:161], v[32:47]
	ds_read_b64_tr_b16 v[84:85], v210 offset:0x1200
	ds_read_b64_tr_b16 v[86:87], v210 offset:0x1a00
	v_mfma_f32_32x32x16_bf16 v[32:47], v[68:71], v[162:165], v[32:47]
	ds_read_b64_tr_b16 v[88:89], v210 offset:0x2200
	ds_read_b64_tr_b16 v[90:91], v210 offset:0x2a00
	v_mfma_f32_32x32x16_bf16 v[32:47], v[64:67], v[206:209], v[32:47]
	ds_read_b64_tr_b16 v[92:93], v210 offset:0x3200
	ds_read_b64_tr_b16 v[94:95], v210 offset:0x3a00
	s_waitcnt lgkmcnt(0)
	v_mfma_f32_32x32x16_bf16 v[48:63], v[76:79], v[80:83], v[48:63]
	ds_read_b64_tr_b16 v[80:81], v210 offset:0x400
	ds_read_b64_tr_b16 v[82:83], v210 offset:0xc00
	v_mfma_f32_32x32x16_bf16 v[48:63], v[72:75], v[84:87], v[48:63]
	ds_read_b64_tr_b16 v[84:85], v210 offset:0x1400
	ds_read_b64_tr_b16 v[86:87], v210 offset:0x1c00
	v_mfma_f32_32x32x16_bf16 v[48:63], v[68:71], v[88:91], v[48:63]
	ds_read_b64_tr_b16 v[88:89], v210 offset:0x2400
	ds_read_b64_tr_b16 v[90:91], v210 offset:0x2c00
	v_mfma_f32_32x32x16_bf16 v[48:63], v[64:67], v[92:95], v[48:63]
	ds_read_b64_tr_b16 v[92:93], v210 offset:0x3400
	ds_read_b64_tr_b16 v[94:95], v210 offset:0x3c00
	s_waitcnt lgkmcnt(0)
	v_mfma_f32_32x32x16_bf16 v[16:31], v[76:79], v[80:83], v[16:31]
	ds_read_b64_tr_b16 v[80:81], v210 offset:0x600
	ds_read_b64_tr_b16 v[82:83], v210 offset:0xe00
	v_mfma_f32_32x32x16_bf16 v[16:31], v[72:75], v[84:87], v[16:31]
	ds_read_b64_tr_b16 v[84:85], v210 offset:0x1600
	ds_read_b64_tr_b16 v[86:87], v210 offset:0x1e00
	v_mfma_f32_32x32x16_bf16 v[16:31], v[68:71], v[88:91], v[16:31]
	ds_read_b64_tr_b16 v[88:89], v210 offset:0x2600
	ds_read_b64_tr_b16 v[90:91], v210 offset:0x2e00
	v_mfma_f32_32x32x16_bf16 v[16:31], v[64:67], v[92:95], v[16:31]
	ds_read_b64_tr_b16 v[92:93], v210 offset:0x3600
	ds_read_b64_tr_b16 v[94:95], v210 offset:0x3e00
	s_waitcnt lgkmcnt(0)
	s_add_i32 s36, s57, -2
	s_and_b32 s74, s36, 1
	s_lshl_b32 s36, s74, 14
	s_lshl_b32 s42, s74, 13
	s_add_i32 s42, s42, 0x14000
	v_add3_u32 v210, s36, v222, v221
	v_add3_u32 v211, s36, v223, v221
	v_add3_u32 v212, s36, v224, v221
	v_add3_u32 v213, s36, v225, v221
	ds_read_b128 v[240:243], v210 offset:49152
	ds_read_b128 v[244:247], v211 offset:49152
	ds_read_b128 v[248:251], v212 offset:49152
	ds_read_b128 v[236:239], v213 offset:49152
	v_mfma_f32_32x32x16_bf16 v[0:15], v[76:79], v[80:83], v[0:15]
	v_mfma_f32_32x32x16_bf16 v[0:15], v[72:75], v[84:87], v[0:15]
	v_mfma_f32_32x32x16_bf16 v[0:15], v[68:71], v[88:91], v[0:15]
	v_mfma_f32_32x32x16_bf16 v[0:15], v[64:67], v[92:95], v[0:15]
	s_setprio 0
	s_branch .Lqkb_entry

.Lqkb_entry:
	ds_read_b128 v[64:67], v210 offset:49280
	ds_read_b128 v[68:71], v211 offset:49280
	ds_read_b128 v[72:75], v212 offset:49280
	ds_read_b128 v[76:79], v213 offset:49280
	v_add3_u32 v234, s42, v227, v226
	v_add3_u32 v235, s42, v228, v226
	s_waitcnt lgkmcnt(7)
	v_mfma_f32_32x32x16_bf16 v[80:95], v[240:243], v[98:101], 0
	ds_read_b128 v[240:243], v234
	s_waitcnt lgkmcnt(7)
	v_mfma_f32_32x32x16_bf16 v[80:95], v[244:247], v[102:105], v[80:95]
	ds_read_b128 v[244:247], v235
	v_add3_u32 v234, s42, v229, v226
	v_add3_u32 v235, s42, v230, v226
	s_waitcnt lgkmcnt(7)
	v_mfma_f32_32x32x16_bf16 v[80:95], v[248:251], v[106:109], v[80:95]
	ds_read_b128 v[248:251], v234
	s_waitcnt lgkmcnt(7)
	v_mfma_f32_32x32x16_bf16 v[80:95], v[236:239], v[110:113], v[80:95]
	ds_read_b128 v[236:239], v235
	s_waitcnt lgkmcnt(7)
	v_mfma_f32_32x32x16_bf16 v[80:95], v[64:67], v[114:117], v[80:95]
	ds_read_b128 v[64:67], v210 offset:57344
	s_waitcnt lgkmcnt(7)
	v_mfma_f32_32x32x16_bf16 v[80:95], v[68:71], v[118:121], v[80:95]
	s_waitcnt lgkmcnt(6)
	v_mfma_f32_32x32x16_bf16 v[80:95], v[72:75], v[122:125], v[80:95]
	s_waitcnt lgkmcnt(5)
	v_mfma_f32_32x32x16_bf16 v[80:95], v[76:79], v[126:129], v[80:95]
	s_waitcnt lgkmcnt(4)
	v_mfma_f32_32x32x16_bf16 v[80:95], v[240:243], v[130:133], v[80:95]
	ds_read_b128 v[240:243], v211 offset:57344
	s_waitcnt lgkmcnt(4)
	v_mfma_f32_32x32x16_bf16 v[80:95], v[244:247], v[138:141], v[80:95]
	ds_read_b128 v[244:247], v212 offset:57344
	s_waitcnt lgkmcnt(4)
	v_mfma_f32_32x32x16_bf16 v[80:95], v[248:251], v[134:137], v[80:95]
	ds_read_b128 v[248:251], v213 offset:57344
	s_waitcnt lgkmcnt(4)
	v_mfma_f32_32x32x16_bf16 v[80:95], v[236:239], v[142:145], v[80:95]
	ds_read_b128 v[236:239], v210 offset:57472
	s_waitcnt lgkmcnt(4)
	v_mfma_f32_32x32x16_bf16 v[64:79], v[64:67], v[98:101], 0
	s_waitcnt lgkmcnt(3)
	v_mfma_f32_32x32x16_bf16 v[64:79], v[240:243], v[102:105], v[64:79]
	ds_read_b128 v[240:243], v211 offset:57472
	s_waitcnt lgkmcnt(3)
	v_mfma_f32_32x32x16_bf16 v[64:79], v[244:247], v[106:109], v[64:79]
	ds_read_b128 v[244:247], v212 offset:57472
	v_add3_u32 v210, s42, v227, v226
	s_waitcnt lgkmcnt(3)
	v_mfma_f32_32x32x16_bf16 v[64:79], v[248:251], v[110:113], v[64:79]
	ds_read_b128 v[248:251], v213 offset:57472
	v_add3_u32 v211, s42, v228, v226
	s_waitcnt lgkmcnt(3)
	v_mfma_f32_32x32x16_bf16 v[64:79], v[236:239], v[114:117], v[64:79]
	ds_read_b128 v[236:239], v210 offset:4096
	v_add3_u32 v212, s42, v229, v226
	s_waitcnt lgkmcnt(3)
	v_mfma_f32_32x32x16_bf16 v[64:79], v[240:243], v[118:121], v[64:79]
	ds_read_b128 v[240:243], v211 offset:4096
	v_add3_u32 v213, s42, v230, v226
	s_waitcnt lgkmcnt(3)
	v_mfma_f32_32x32x16_bf16 v[64:79], v[244:247], v[122:125], v[64:79]
	ds_read_b128 v[244:247], v212 offset:4096
	s_waitcnt lgkmcnt(3)
	v_mfma_f32_32x32x16_bf16 v[64:79], v[248:251], v[126:129], v[64:79]
	ds_read_b128 v[248:251], v213 offset:4096
	s_waitcnt lgkmcnt(3)
	v_mfma_f32_32x32x16_bf16 v[64:79], v[236:239], v[130:133], v[64:79]
	s_waitcnt lgkmcnt(2)
	v_mfma_f32_32x32x16_bf16 v[64:79], v[240:243], v[138:141], v[64:79]
	s_waitcnt lgkmcnt(1)
	v_mfma_f32_32x32x16_bf16 v[64:79], v[244:247], v[134:137], v[64:79]
	s_waitcnt lgkmcnt(0)
	v_mfma_f32_32x32x16_bf16 v[64:79], v[248:251], v[142:145], v[64:79]
	s_add_i32 s36, s8, 63
	s_cmp_le_i32 s36, s2
	s_cselect_b64 s[36:37], -1, 0
	s_cmp_gt_i32 s8, s55
	s_cselect_b64 s[42:43], -1, 0
	s_and_b64 s[36:37], s[36:37], s[42:43]
	s_and_b64 vcc, exec, s[36:37]
	s_cbranch_vccnz .LBB0_150
	v_add_u32_e32 v210, s69, v231
	v_cmp_gt_u32_e32 vcc, s66, v210
	v_add_u32_e32 v211, 0xffefffe0, v210
	s_nop 0
	v_cndmask_b32_e32 v80, v214, v80, vcc
	v_cmp_lt_u32_e32 vcc, s67, v211
	v_add_u32_e32 v211, 0xffefffff, v210
	s_nop 0
	v_cndmask_b32_e32 v64, v214, v64, vcc
	v_cmp_lt_u32_e32 vcc, s67, v211
	v_add_u32_e32 v211, 0xffefffdf, v210
	s_nop 0
	v_cndmask_b32_e32 v81, v214, v81, vcc
	v_cmp_lt_u32_e32 vcc, s67, v211
	v_add_u32_e32 v211, 0xffeffffe, v210
	s_nop 0
	v_cndmask_b32_e32 v65, v214, v65, vcc
	v_cmp_lt_u32_e32 vcc, s67, v211
	v_add_u32_e32 v211, 0xffefffde, v210
	s_nop 0
	v_cndmask_b32_e32 v82, v214, v82, vcc
	v_cmp_lt_u32_e32 vcc, s67, v211
	v_add_u32_e32 v211, 0xffeffffd, v210
	s_nop 0
	v_cndmask_b32_e32 v66, v214, v66, vcc
	v_cmp_lt_u32_e32 vcc, s67, v211
	v_add_u32_e32 v211, 0xffefffdd, v210
	s_nop 0
	v_cndmask_b32_e32 v83, v214, v83, vcc
	v_cmp_lt_u32_e32 vcc, s67, v211
	v_add_u32_e32 v211, 0xffeffff8, v210
	s_nop 0
	v_cndmask_b32_e32 v67, v214, v67, vcc
	v_cmp_lt_u32_e32 vcc, s67, v211
	v_add_u32_e32 v211, 0xffefffd8, v210
	s_nop 0
	v_cndmask_b32_e32 v84, v214, v84, vcc
	v_cmp_lt_u32_e32 vcc, s67, v211
	v_add_u32_e32 v211, 0xffeffff7, v210
	s_nop 0
	v_cndmask_b32_e32 v68, v214, v68, vcc
	v_cmp_lt_u32_e32 vcc, s67, v211
	v_add_u32_e32 v211, 0xffefffd7, v210
	s_nop 0
	v_cndmask_b32_e32 v85, v214, v85, vcc
	v_cmp_lt_u32_e32 vcc, s67, v211
	v_add_u32_e32 v211, 0xffeffff6, v210
	s_nop 0
	v_cndmask_b32_e32 v69, v214, v69, vcc
	v_cmp_lt_u32_e32 vcc, s67, v211
	v_add_u32_e32 v211, 0xffefffd6, v210
	s_nop 0
	v_cndmask_b32_e32 v86, v214, v86, vcc
	v_cmp_lt_u32_e32 vcc, s67, v211
	v_add_u32_e32 v211, 0xffeffff5, v210
	s_nop 0
	v_cndmask_b32_e32 v70, v214, v70, vcc
	v_cmp_lt_u32_e32 vcc, s67, v211
	v_add_u32_e32 v211, 0xffefffd5, v210
	s_nop 0
	v_cndmask_b32_e32 v87, v214, v87, vcc
	v_cmp_lt_u32_e32 vcc, s67, v211
	v_add_u32_e32 v211, 0xffeffff0, v210
	s_nop 0
	v_cndmask_b32_e32 v71, v214, v71, vcc
	v_cmp_lt_u32_e32 vcc, s67, v211
	v_add_u32_e32 v211, 0xffefffd0, v210
	s_nop 0
	v_cndmask_b32_e32 v88, v214, v88, vcc
	v_cmp_lt_u32_e32 vcc, s67, v211
	v_add_u32_e32 v211, 0xffefffef, v210
	s_nop 0
	v_cndmask_b32_e32 v72, v214, v72, vcc
	v_cmp_lt_u32_e32 vcc, s67, v211
	v_add_u32_e32 v211, 0xffefffcf, v210
	s_nop 0
	v_cndmask_b32_e32 v89, v214, v89, vcc
	v_cmp_lt_u32_e32 vcc, s67, v211
	v_add_u32_e32 v211, 0xffefffee, v210
	s_nop 0
	v_cndmask_b32_e32 v73, v214, v73, vcc
	v_cmp_lt_u32_e32 vcc, s67, v211
	v_add_u32_e32 v211, 0xffefffce, v210
	s_nop 0
	v_cndmask_b32_e32 v90, v214, v90, vcc
	v_cmp_lt_u32_e32 vcc, s67, v211
	v_add_u32_e32 v211, 0xffefffed, v210
	s_nop 0
	v_cndmask_b32_e32 v74, v214, v74, vcc
	v_cmp_lt_u32_e32 vcc, s67, v211
	v_add_u32_e32 v211, 0xffefffcd, v210
	s_nop 0
	v_cndmask_b32_e32 v91, v214, v91, vcc
	v_cmp_lt_u32_e32 vcc, s67, v211
	v_add_u32_e32 v211, 0xffefffe8, v210
	s_nop 0
	v_cndmask_b32_e32 v75, v214, v75, vcc
	v_cmp_lt_u32_e32 vcc, s67, v211
	v_add_u32_e32 v211, 0xffefffc8, v210
	s_nop 0
	v_cndmask_b32_e32 v92, v214, v92, vcc
	v_cmp_lt_u32_e32 vcc, s67, v211
	v_add_u32_e32 v211, 0xffefffe7, v210
	s_nop 0
	v_cndmask_b32_e32 v76, v214, v76, vcc
	v_cmp_lt_u32_e32 vcc, s67, v211
	v_add_u32_e32 v211, 0xffefffc7, v210
	s_nop 0
	v_cndmask_b32_e32 v93, v214, v93, vcc
	v_cmp_lt_u32_e32 vcc, s67, v211
	v_add_u32_e32 v211, 0xffefffe6, v210
	s_nop 0
	v_cndmask_b32_e32 v77, v214, v77, vcc
	v_cmp_lt_u32_e32 vcc, s67, v211
	v_add_u32_e32 v211, 0xffefffc6, v210
	s_nop 0
	v_cndmask_b32_e32 v94, v214, v94, vcc
	v_cmp_lt_u32_e32 vcc, s67, v211
	v_add_u32_e32 v211, 0xffefffe5, v210
	v_add_u32_e32 v210, 0xffefffc5, v210
	v_cndmask_b32_e32 v78, v214, v78, vcc
	v_cmp_lt_u32_e32 vcc, s67, v211
	s_nop 1
	v_cndmask_b32_e32 v95, v214, v95, vcc
	v_cmp_lt_u32_e32 vcc, s67, v210
	s_nop 1
	v_cndmask_b32_e32 v79, v214, v79, vcc
